# nt hint on epilogue stores whose consumer is a later phase (P7 U, P8 out, P5 out) to keep GEMM operand tiles in L2
# speedup vs baseline: 1.0017x; 1.0017x over previous
; __device__ __forceinline__ unsigned cvt_pk_bf16(float lo, float hi) { unsigned r; asm volatile("v_cvt_pk_bf16_f32 %0, %1, %2" : "=v"(r) : "v"(lo), "v"(hi)); return r; }
;     __device__ __forceinline__ void operator()(const f32x4 (&acc)[2][2][4][2], const Unit& u, int wr, int wc, int fr, int fq) const {
;         const int row0 = u.pm * BM + wr * 64 + fr, col0 = u.pn * BM + wc * 32 + 4 * fq, b = (u.pm * BM) >> 12;
;         f32x4 gv[2][2], Gv[2][2];
; #pragma unroll
;         for (int bj = 0; bj < 2; ++bj)
; #pragma unroll
;             for (int n = 0; n < 2; ++n) { const int c = col0 + bj * HALF + n * 16; gv[bj][n] = *(const f32x4*)(mod + (size_t)b * 12288 + 2 * 2048 + c);
;                 Gv[bj][n] = *(const f32x4*)(g2 + c) * (*(const f32x4*)(mod + (size_t)b * 12288 + 4 * 2048 + c) + 1.0f); }
;         float* prow = part + (size_t)(u.pn * 4 + wc) * 16384;
; #pragma unroll
;         for (int ai = 0; ai < 2; ++ai)
; #pragma unroll
;             for (int m = 0; m < 4; ++m) { const int row = row0 + ai * HALF + m * 16; const size_t off = (size_t)row * 2048 + col0; float ss = 0.f;
; #pragma unroll
;                 for (int bj = 0; bj < 2; ++bj)
; #pragma unroll
;                     for (int n = 0; n < 2; ++n) { const f32x4 bs = __builtin_nontemporal_load((const f32x4*)(base + off + bj * HALF + n * 16)); const f32x4 x1 = bs + gv[bj][n] * acc[ai][bj][m][n];
;                         *(f32x4*)(out + off + bj * HALF + n * 16) = x1; ss += (x1.x * x1.x + x1.y * x1.y) + (x1.z * x1.z + x1.w * x1.w);
;                         const f32x4 hh = x1 * Gv[bj][n]; u32x2 w; w.x = cvt_pk_bf16(hh.x, hh.y); w.y = cvt_pk_bf16(hh.z, hh.w); *(u32x2*)(A2 + off + bj * HALF + n * 16) = w; }
.LBB0_897:
	v_readlane_b32 s98, v236, 7
	v_readlane_b32 s99, v236, 8
	v_readlane_b32 s76, v236, 35
	v_readlane_b32 s77, v236, 36
	s_ashr_i32 s25, s36, 4
	s_mul_hi_i32 s27, s25, 0xc000
	s_mul_i32 s25, s25, 0xc000
	s_add_u32 s38, s68, s25
	s_addc_u32 s39, s69, s27
	s_add_u32 s40, s38, 0x8000
	s_addc_u32 s41, s39, 0
	s_add_u32 s38, s38, 0x4000
	s_addc_u32 s39, s39, 0
	v_lshl_add_u32 v164, s36, 8, v166
	v_lshl_or_b32 v165, s34, 8, v168
	v_lshlrev_b32_e32 v173, 2, v165
	v_xor_b32_e32 v216, 16, v172
	v_xor_b32_e32 v217, 32, v172
	v_lshlrev_b32_e32 v216, 2, v216
	v_lshlrev_b32_e32 v217, 2, v217
	global_load_dwordx4 v[72:75], v173, s[38:39]
	global_load_dwordx4 v[84:87], v173, s[38:39] offset:64
	global_load_dwordx4 v[92:95], v173, s[38:39] offset:512
	global_load_dwordx4 v[96:99], v173, s[38:39] offset:576
	global_load_dwordx4 v[156:159], v173, s[40:41]
	global_load_dwordx4 v[160:163], v173, s[40:41] offset:64
	global_load_dwordx4 v[174:177], v173, s[40:41] offset:512
	global_load_dwordx4 v[178:181], v173, s[40:41] offset:576
	global_load_dwordx4 v[182:185], v173, s[76:77]
	global_load_dwordx4 v[188:191], v173, s[76:77] offset:64
	global_load_dwordx4 v[192:195], v173, s[76:77] offset:512
	global_load_dwordx4 v[196:199], v173, s[76:77] offset:576
	v_lshl_add_u32 v164, v164, 13, v173
	v_mov_b32_e32 v165, v164
	v_lshrrev_b32_e32 v173, 1, v164
	global_load_dwordx4 v[200:203], v164, s[98:99] nt
	global_load_dwordx4 v[204:207], v164, s[98:99] offset:64 nt
	global_load_dwordx4 v[208:211], v164, s[98:99] offset:512 nt
	global_load_dwordx4 v[212:215], v164, s[98:99] offset:576 nt
	v_add_u32_e32 v164, 0x20000, v164
	s_waitcnt vmcnt(4)
	v_pk_add_f32 v[156:157], v[156:157], 1.0 op_sel_hi:[1,0]
	v_pk_add_f32 v[158:159], v[158:159], 1.0 op_sel_hi:[1,0]
	v_pk_mul_f32 v[182:183], v[182:183], v[156:157]
	v_pk_mul_f32 v[184:185], v[184:185], v[158:159]
	v_pk_add_f32 v[160:161], v[160:161], 1.0 op_sel_hi:[1,0]
	v_pk_add_f32 v[162:163], v[162:163], 1.0 op_sel_hi:[1,0]
	v_pk_mul_f32 v[188:189], v[188:189], v[160:161]
	v_pk_mul_f32 v[190:191], v[190:191], v[162:163]
	v_pk_add_f32 v[174:175], v[174:175], 1.0 op_sel_hi:[1,0]
	v_pk_add_f32 v[176:177], v[176:177], 1.0 op_sel_hi:[1,0]
	v_pk_mul_f32 v[192:193], v[192:193], v[174:175]
	v_pk_mul_f32 v[194:195], v[194:195], v[176:177]
	v_pk_add_f32 v[178:179], v[178:179], 1.0 op_sel_hi:[1,0]
	v_pk_add_f32 v[180:181], v[180:181], 1.0 op_sel_hi:[1,0]
	v_pk_mul_f32 v[196:197], v[196:197], v[178:179]
	v_pk_mul_f32 v[198:199], v[198:199], v[180:181]
	global_load_dwordx4 v[156:159], v164, s[98:99] nt
	global_load_dwordx4 v[160:163], v164, s[98:99] offset:64 nt
	global_load_dwordx4 v[174:177], v164, s[98:99] offset:512 nt
	global_load_dwordx4 v[178:181], v164, s[98:99] offset:576 nt
	v_add_u32_e32 v164, 0x20000, v164
	s_waitcnt vmcnt(7)
	v_pk_fma_f32 v[200:201], v[140:141], v[72:73], v[200:201]
	v_pk_fma_f32 v[202:203], v[142:143], v[74:75], v[202:203]
	global_store_dwordx4 v165, v[200:203], s[66:67] nt
	v_pk_mul_f32 v[140:141], v[200:201], v[182:183]
	v_pk_mul_f32 v[142:143], v[202:203], v[184:185]
	v_cvt_pk_bf16_f32 v140, v140, v141
	v_cvt_pk_bf16_f32 v141, v142, v143
	global_store_dwordx2 v173, v[140:141], s[8:9]
	v_mul_f32_e32 v142, v200, v200
	v_fmac_f32_e32 v142, v201, v201
	v_fmac_f32_e32 v142, v202, v202
	v_fmac_f32_e32 v142, v203, v203
	global_load_dwordx4 v[200:203], v164, s[98:99] nt
	s_waitcnt vmcnt(9)
	v_pk_fma_f32 v[204:205], v[136:137], v[84:85], v[204:205]
	v_pk_fma_f32 v[206:207], v[138:139], v[86:87], v[206:207]
	global_store_dwordx4 v165, v[204:207], s[66:67] offset:64 nt
	v_pk_mul_f32 v[136:137], v[204:205], v[188:189]
	v_pk_mul_f32 v[138:139], v[206:207], v[190:191]
	v_cvt_pk_bf16_f32 v136, v136, v137
	v_cvt_pk_bf16_f32 v137, v138, v139
	global_store_dwordx2 v173, v[136:137], s[8:9] offset:32
	v_fmac_f32_e32 v142, v204, v204
	v_fmac_f32_e32 v142, v205, v205
	v_fmac_f32_e32 v142, v206, v206
	v_fmac_f32_e32 v142, v207, v207
	global_load_dwordx4 v[204:207], v164, s[98:99] offset:64 nt
	s_waitcnt vmcnt(11)
	v_pk_fma_f32 v[208:209], v[132:133], v[92:93], v[208:209]
	v_pk_fma_f32 v[210:211], v[134:135], v[94:95], v[210:211]
	global_store_dwordx4 v165, v[208:211], s[66:67] offset:512 nt
	v_pk_mul_f32 v[132:133], v[208:209], v[192:193]
	v_pk_mul_f32 v[134:135], v[210:211], v[194:195]
	v_cvt_pk_bf16_f32 v132, v132, v133
	v_cvt_pk_bf16_f32 v133, v134, v135
	global_store_dwordx2 v173, v[132:133], s[8:9] offset:256
	v_fmac_f32_e32 v142, v208, v208
	v_fmac_f32_e32 v142, v209, v209
	v_fmac_f32_e32 v142, v210, v210
	v_fmac_f32_e32 v142, v211, v211
	global_load_dwordx4 v[208:211], v164, s[98:99] offset:512 nt
	s_waitcnt vmcnt(13)
	v_pk_fma_f32 v[212:213], v[128:129], v[96:97], v[212:213]
	v_pk_fma_f32 v[214:215], v[130:131], v[98:99], v[214:215]
	global_store_dwordx4 v165, v[212:215], s[66:67] offset:576 nt
	v_pk_mul_f32 v[128:129], v[212:213], v[196:197]
	v_pk_mul_f32 v[130:131], v[214:215], v[198:199]
	v_cvt_pk_bf16_f32 v128, v128, v129
	v_cvt_pk_bf16_f32 v129, v130, v131
	global_store_dwordx2 v173, v[128:129], s[8:9] offset:288
	v_fmac_f32_e32 v142, v212, v212
	v_fmac_f32_e32 v142, v213, v213
	v_fmac_f32_e32 v142, v214, v214
	v_fmac_f32_e32 v142, v215, v215
	v_add_u32_e32 v165, 0x20000, v165
	v_lshrrev_b32_e32 v173, 1, v165
	global_load_dwordx4 v[212:215], v164, s[98:99] offset:576 nt
	v_add_u32_e32 v164, 0x20000, v164
	s_waitcnt vmcnt(15)
; __device__ __forceinline__ unsigned cvt_pk_bf16(float lo, float hi) { unsigned r; asm volatile("v_cvt_pk_bf16_f32 %0, %1, %2" : "=v"(r) : "v"(lo), "v"(hi)); return r; }
;     __device__ __forceinline__ void operator()(const f32x4 (&acc)[2][2][4][2], const Unit& u, int wr, int wc, int fr, int fq) const {
;     ...
;         for (int ai = 0; ai < 2; ++ai)
; #pragma unroll
;             for (int m = 0; m < 4; ++m) { const int row = row0 + ai * HALF + m * 16; const size_t off = (size_t)row * 2048 + col0; float ss = 0.f;
; #pragma unroll
;                 for (int bj = 0; bj < 2; ++bj)
; #pragma unroll
;                     for (int n = 0; n < 2; ++n) { const f32x4 bs = __builtin_nontemporal_load((const f32x4*)(base + off + bj * HALF + n * 16)); const f32x4 x1 = bs + gv[bj][n] * acc[ai][bj][m][n];
;                         *(f32x4*)(out + off + bj * HALF + n * 16) = x1; ss += (x1.x * x1.x + x1.y * x1.y) + (x1.z * x1.z + x1.w * x1.w);
;                         const f32x4 hh = x1 * Gv[bj][n]; u32x2 w; w.x = cvt_pk_bf16(hh.x, hh.y); w.y = cvt_pk_bf16(hh.z, hh.w); *(u32x2*)(A2 + off + bj * HALF + n * 16) = w; }
	v_pk_fma_f32 v[156:157], v[124:125], v[72:73], v[156:157]
	v_pk_fma_f32 v[158:159], v[126:127], v[74:75], v[158:159]
	global_store_dwordx4 v165, v[156:159], s[66:67] nt
	v_pk_mul_f32 v[124:125], v[156:157], v[182:183]
	v_pk_mul_f32 v[126:127], v[158:159], v[184:185]
	v_cvt_pk_bf16_f32 v124, v124, v125
	v_cvt_pk_bf16_f32 v125, v126, v127
	global_store_dwordx2 v173, v[124:125], s[8:9]
	v_mul_f32_e32 v126, v156, v156
	v_fmac_f32_e32 v126, v157, v157
	v_fmac_f32_e32 v126, v158, v158
	v_fmac_f32_e32 v126, v159, v159
	global_load_dwordx4 v[156:159], v164, s[98:99] nt
	s_waitcnt vmcnt(17)
	v_pk_fma_f32 v[160:161], v[120:121], v[84:85], v[160:161]
	v_pk_fma_f32 v[162:163], v[122:123], v[86:87], v[162:163]
	global_store_dwordx4 v165, v[160:163], s[66:67] offset:64 nt
	v_pk_mul_f32 v[120:121], v[160:161], v[188:189]
	v_pk_mul_f32 v[122:123], v[162:163], v[190:191]
	v_cvt_pk_bf16_f32 v120, v120, v121
	v_cvt_pk_bf16_f32 v121, v122, v123
	global_store_dwordx2 v173, v[120:121], s[8:9] offset:32
	v_fmac_f32_e32 v126, v160, v160
	v_fmac_f32_e32 v126, v161, v161
	v_fmac_f32_e32 v126, v162, v162
	v_fmac_f32_e32 v126, v163, v163
	global_load_dwordx4 v[160:163], v164, s[98:99] offset:64 nt
	s_waitcnt vmcnt(19)
	v_pk_fma_f32 v[174:175], v[116:117], v[92:93], v[174:175]
	v_pk_fma_f32 v[176:177], v[118:119], v[94:95], v[176:177]
	global_store_dwordx4 v165, v[174:177], s[66:67] offset:512 nt
	v_pk_mul_f32 v[116:117], v[174:175], v[192:193]
	v_pk_mul_f32 v[118:119], v[176:177], v[194:195]
	v_cvt_pk_bf16_f32 v116, v116, v117
	v_cvt_pk_bf16_f32 v117, v118, v119
	global_store_dwordx2 v173, v[116:117], s[8:9] offset:256
	v_fmac_f32_e32 v126, v174, v174
	v_fmac_f32_e32 v126, v175, v175
	v_fmac_f32_e32 v126, v176, v176
	v_fmac_f32_e32 v126, v177, v177
	global_load_dwordx4 v[174:177], v164, s[98:99] offset:512 nt
	s_waitcnt vmcnt(21)
	v_pk_fma_f32 v[178:179], v[112:113], v[96:97], v[178:179]
	v_pk_fma_f32 v[180:181], v[114:115], v[98:99], v[180:181]
	global_store_dwordx4 v165, v[178:181], s[66:67] offset:576 nt
	v_pk_mul_f32 v[112:113], v[178:179], v[196:197]
	v_pk_mul_f32 v[114:115], v[180:181], v[198:199]
	v_cvt_pk_bf16_f32 v112, v112, v113
	v_cvt_pk_bf16_f32 v113, v114, v115
	global_store_dwordx2 v173, v[112:113], s[8:9] offset:288
	v_fmac_f32_e32 v126, v178, v178
	v_fmac_f32_e32 v126, v179, v179
	v_fmac_f32_e32 v126, v180, v180
	v_fmac_f32_e32 v126, v181, v181
	v_add_u32_e32 v165, 0x20000, v165
	v_lshrrev_b32_e32 v173, 1, v165
	global_load_dwordx4 v[178:181], v164, s[98:99] offset:576 nt
	v_add_u32_e32 v164, 0xa0000, v164
	s_waitcnt vmcnt(21)
	v_pk_fma_f32 v[200:201], v[108:109], v[72:73], v[200:201]
	v_pk_fma_f32 v[202:203], v[110:111], v[74:75], v[202:203]
	global_store_dwordx4 v165, v[200:203], s[66:67] nt
	v_pk_mul_f32 v[108:109], v[200:201], v[182:183]
	v_pk_mul_f32 v[110:111], v[202:203], v[184:185]
	v_cvt_pk_bf16_f32 v108, v108, v109
	v_cvt_pk_bf16_f32 v109, v110, v111
	global_store_dwordx2 v173, v[108:109], s[8:9]
	v_mul_f32_e32 v110, v200, v200
	v_fmac_f32_e32 v110, v201, v201
	v_fmac_f32_e32 v110, v202, v202
	v_fmac_f32_e32 v110, v203, v203
	global_load_dwordx4 v[200:203], v164, s[98:99] nt
	s_waitcnt vmcnt(21)
	v_pk_fma_f32 v[204:205], v[104:105], v[84:85], v[204:205]
	v_pk_fma_f32 v[206:207], v[106:107], v[86:87], v[206:207]
	global_store_dwordx4 v165, v[204:207], s[66:67] offset:64 nt
	v_pk_mul_f32 v[104:105], v[204:205], v[188:189]
	v_pk_mul_f32 v[106:107], v[206:207], v[190:191]
	v_cvt_pk_bf16_f32 v104, v104, v105
	v_cvt_pk_bf16_f32 v105, v106, v107
	global_store_dwordx2 v173, v[104:105], s[8:9] offset:32
	v_fmac_f32_e32 v110, v204, v204
	v_fmac_f32_e32 v110, v205, v205
	v_fmac_f32_e32 v110, v206, v206
	v_fmac_f32_e32 v110, v207, v207
	global_load_dwordx4 v[204:207], v164, s[98:99] offset:64 nt
	s_waitcnt vmcnt(21)
	v_pk_fma_f32 v[208:209], v[100:101], v[92:93], v[208:209]
	v_pk_fma_f32 v[210:211], v[102:103], v[94:95], v[210:211]
	global_store_dwordx4 v165, v[208:211], s[66:67] offset:512 nt
	v_pk_mul_f32 v[100:101], v[208:209], v[192:193]
	v_pk_mul_f32 v[102:103], v[210:211], v[194:195]
	v_cvt_pk_bf16_f32 v100, v100, v101
	v_cvt_pk_bf16_f32 v101, v102, v103
	global_store_dwordx2 v173, v[100:101], s[8:9] offset:256
	v_fmac_f32_e32 v110, v208, v208
	v_fmac_f32_e32 v110, v209, v209
	v_fmac_f32_e32 v110, v210, v210
	v_fmac_f32_e32 v110, v211, v211
	global_load_dwordx4 v[208:211], v164, s[98:99] offset:512 nt
	s_waitcnt vmcnt(21)
	v_pk_fma_f32 v[212:213], v[88:89], v[96:97], v[212:213]
	v_pk_fma_f32 v[214:215], v[90:91], v[98:99], v[214:215]
	global_store_dwordx4 v165, v[212:215], s[66:67] offset:576 nt
	v_pk_mul_f32 v[88:89], v[212:213], v[196:197]
	v_pk_mul_f32 v[90:91], v[214:215], v[198:199]
	v_cvt_pk_bf16_f32 v88, v88, v89
	v_cvt_pk_bf16_f32 v89, v90, v91
	global_store_dwordx2 v173, v[88:89], s[8:9] offset:288
	v_fmac_f32_e32 v110, v212, v212
	v_fmac_f32_e32 v110, v213, v213
	v_fmac_f32_e32 v110, v214, v214
	v_fmac_f32_e32 v110, v215, v215
	v_add_u32_e32 v165, 0x20000, v165
	v_lshrrev_b32_e32 v173, 1, v165
	global_load_dwordx4 v[212:215], v164, s[98:99] offset:576 nt
	v_add_u32_e32 v164, 0x20000, v164
	s_waitcnt vmcnt(21)
	v_pk_fma_f32 v[156:157], v[80:81], v[72:73], v[156:157]
	v_pk_fma_f32 v[158:159], v[82:83], v[74:75], v[158:159]
	global_store_dwordx4 v165, v[156:159], s[66:67] nt
	v_pk_mul_f32 v[80:81], v[156:157], v[182:183]
	v_pk_mul_f32 v[82:83], v[158:159], v[184:185]
	v_cvt_pk_bf16_f32 v80, v80, v81
	v_cvt_pk_bf16_f32 v81, v82, v83
	global_store_dwordx2 v173, v[80:81], s[8:9]
	v_mul_f32_e32 v82, v156, v156
	v_fmac_f32_e32 v82, v157, v157
	v_fmac_f32_e32 v82, v158, v158
	v_fmac_f32_e32 v82, v159, v159
	global_load_dwordx4 v[156:159], v164, s[98:99] nt
	s_waitcnt vmcnt(21)
; __device__ __forceinline__ unsigned cvt_pk_bf16(float lo, float hi) { unsigned r; asm volatile("v_cvt_pk_bf16_f32 %0, %1, %2" : "=v"(r) : "v"(lo), "v"(hi)); return r; }
;     __device__ __forceinline__ void operator()(const f32x4 (&acc)[2][2][4][2], const Unit& u, int wr, int wc, int fr, int fq) const {
;     ...
;         for (int ai = 0; ai < 2; ++ai)
; #pragma unroll
;             for (int m = 0; m < 4; ++m) { const int row = row0 + ai * HALF + m * 16; const size_t off = (size_t)row * 2048 + col0; float ss = 0.f;
; #pragma unroll
;                 for (int bj = 0; bj < 2; ++bj)
; #pragma unroll
;                     for (int n = 0; n < 2; ++n) { const f32x4 bs = __builtin_nontemporal_load((const f32x4*)(base + off + bj * HALF + n * 16)); const f32x4 x1 = bs + gv[bj][n] * acc[ai][bj][m][n];
;                         *(f32x4*)(out + off + bj * HALF + n * 16) = x1; ss += (x1.x * x1.x + x1.y * x1.y) + (x1.z * x1.z + x1.w * x1.w);
;                         const f32x4 hh = x1 * Gv[bj][n]; u32x2 w; w.x = cvt_pk_bf16(hh.x, hh.y); w.y = cvt_pk_bf16(hh.z, hh.w); *(u32x2*)(A2 + off + bj * HALF + n * 16) = w; }
	v_pk_fma_f32 v[160:161], v[76:77], v[84:85], v[160:161]
	v_pk_fma_f32 v[162:163], v[78:79], v[86:87], v[162:163]
	global_store_dwordx4 v165, v[160:163], s[66:67] offset:64 nt
	v_pk_mul_f32 v[76:77], v[160:161], v[188:189]
	v_pk_mul_f32 v[78:79], v[162:163], v[190:191]
	v_cvt_pk_bf16_f32 v76, v76, v77
	v_cvt_pk_bf16_f32 v77, v78, v79
	global_store_dwordx2 v173, v[76:77], s[8:9] offset:32
	v_fmac_f32_e32 v82, v160, v160
	v_fmac_f32_e32 v82, v161, v161
	v_fmac_f32_e32 v82, v162, v162
	v_fmac_f32_e32 v82, v163, v163
	global_load_dwordx4 v[160:163], v164, s[98:99] offset:64 nt
	s_waitcnt vmcnt(21)
	v_pk_fma_f32 v[174:175], v[68:69], v[92:93], v[174:175]
	v_pk_fma_f32 v[176:177], v[70:71], v[94:95], v[176:177]
	global_store_dwordx4 v165, v[174:177], s[66:67] offset:512 nt
	v_pk_mul_f32 v[68:69], v[174:175], v[192:193]
	v_pk_mul_f32 v[70:71], v[176:177], v[194:195]
	v_cvt_pk_bf16_f32 v68, v68, v69
	v_cvt_pk_bf16_f32 v69, v70, v71
	global_store_dwordx2 v173, v[68:69], s[8:9] offset:256
	v_fmac_f32_e32 v82, v174, v174
	v_fmac_f32_e32 v82, v175, v175
	v_fmac_f32_e32 v82, v176, v176
	v_fmac_f32_e32 v82, v177, v177
	global_load_dwordx4 v[174:177], v164, s[98:99] offset:512 nt
	s_waitcnt vmcnt(21)
	v_pk_fma_f32 v[178:179], v[64:65], v[96:97], v[178:179]
	v_pk_fma_f32 v[180:181], v[66:67], v[98:99], v[180:181]
	global_store_dwordx4 v165, v[178:181], s[66:67] offset:576 nt
	v_pk_mul_f32 v[64:65], v[178:179], v[196:197]
	v_pk_mul_f32 v[66:67], v[180:181], v[198:199]
	v_cvt_pk_bf16_f32 v64, v64, v65
	v_cvt_pk_bf16_f32 v65, v66, v67
	global_store_dwordx2 v173, v[64:65], s[8:9] offset:288
	v_fmac_f32_e32 v82, v178, v178
	v_fmac_f32_e32 v82, v179, v179
	v_fmac_f32_e32 v82, v180, v180
	v_fmac_f32_e32 v82, v181, v181
	v_add_u32_e32 v165, 0xa0000, v165
	v_lshrrev_b32_e32 v173, 1, v165
	global_load_dwordx4 v[178:181], v164, s[98:99] offset:576 nt
	v_add_u32_e32 v164, 0x20000, v164
	s_waitcnt vmcnt(21)
	v_pk_fma_f32 v[200:201], v[60:61], v[72:73], v[200:201]
	v_pk_fma_f32 v[202:203], v[62:63], v[74:75], v[202:203]
	global_store_dwordx4 v165, v[200:203], s[66:67] nt
	v_pk_mul_f32 v[60:61], v[200:201], v[182:183]
	v_pk_mul_f32 v[62:63], v[202:203], v[184:185]
	v_cvt_pk_bf16_f32 v60, v60, v61
	v_cvt_pk_bf16_f32 v61, v62, v63
	global_store_dwordx2 v173, v[60:61], s[8:9]
	v_mul_f32_e32 v62, v200, v200
	v_fmac_f32_e32 v62, v201, v201
	v_fmac_f32_e32 v62, v202, v202
	v_fmac_f32_e32 v62, v203, v203
	global_load_dwordx4 v[200:203], v164, s[98:99] nt
	s_waitcnt vmcnt(21)
	v_pk_fma_f32 v[204:205], v[56:57], v[84:85], v[204:205]
	v_pk_fma_f32 v[206:207], v[58:59], v[86:87], v[206:207]
	global_store_dwordx4 v165, v[204:207], s[66:67] offset:64 nt
	v_pk_mul_f32 v[56:57], v[204:205], v[188:189]
	v_pk_mul_f32 v[58:59], v[206:207], v[190:191]
	v_cvt_pk_bf16_f32 v56, v56, v57
	v_cvt_pk_bf16_f32 v57, v58, v59
	global_store_dwordx2 v173, v[56:57], s[8:9] offset:32
	v_fmac_f32_e32 v62, v204, v204
	v_fmac_f32_e32 v62, v205, v205
	v_fmac_f32_e32 v62, v206, v206
	v_fmac_f32_e32 v62, v207, v207
	global_load_dwordx4 v[204:207], v164, s[98:99] offset:64 nt
	s_waitcnt vmcnt(21)
	v_pk_fma_f32 v[208:209], v[52:53], v[92:93], v[208:209]
	v_pk_fma_f32 v[210:211], v[54:55], v[94:95], v[210:211]
	global_store_dwordx4 v165, v[208:211], s[66:67] offset:512 nt
	v_pk_mul_f32 v[52:53], v[208:209], v[192:193]
	v_pk_mul_f32 v[54:55], v[210:211], v[194:195]
	v_cvt_pk_bf16_f32 v52, v52, v53
	v_cvt_pk_bf16_f32 v53, v54, v55
	global_store_dwordx2 v173, v[52:53], s[8:9] offset:256
	v_fmac_f32_e32 v62, v208, v208
	v_fmac_f32_e32 v62, v209, v209
	v_fmac_f32_e32 v62, v210, v210
	v_fmac_f32_e32 v62, v211, v211
	global_load_dwordx4 v[208:211], v164, s[98:99] offset:512 nt
	s_waitcnt vmcnt(21)
	v_pk_fma_f32 v[212:213], v[48:49], v[96:97], v[212:213]
	v_pk_fma_f32 v[214:215], v[50:51], v[98:99], v[214:215]
	global_store_dwordx4 v165, v[212:215], s[66:67] offset:576 nt
	v_pk_mul_f32 v[48:49], v[212:213], v[196:197]
	v_pk_mul_f32 v[50:51], v[214:215], v[198:199]
	v_cvt_pk_bf16_f32 v48, v48, v49
	v_cvt_pk_bf16_f32 v49, v50, v51
	global_store_dwordx2 v173, v[48:49], s[8:9] offset:288
	v_fmac_f32_e32 v62, v212, v212
	v_fmac_f32_e32 v62, v213, v213
	v_fmac_f32_e32 v62, v214, v214
	v_fmac_f32_e32 v62, v215, v215
	v_add_u32_e32 v165, 0x20000, v165
	v_lshrrev_b32_e32 v173, 1, v165
	global_load_dwordx4 v[212:215], v164, s[98:99] offset:576 nt
	v_add_u32_e32 v164, 0x20000, v164
	s_waitcnt vmcnt(21)
	v_pk_fma_f32 v[156:157], v[44:45], v[72:73], v[156:157]
	v_pk_fma_f32 v[158:159], v[46:47], v[74:75], v[158:159]
	global_store_dwordx4 v165, v[156:159], s[66:67] nt
	v_pk_mul_f32 v[44:45], v[156:157], v[182:183]
	v_pk_mul_f32 v[46:47], v[158:159], v[184:185]
	v_cvt_pk_bf16_f32 v44, v44, v45
	v_cvt_pk_bf16_f32 v45, v46, v47
	global_store_dwordx2 v173, v[44:45], s[8:9]
	v_mul_f32_e32 v46, v156, v156
	v_fmac_f32_e32 v46, v157, v157
	v_fmac_f32_e32 v46, v158, v158
	v_fmac_f32_e32 v46, v159, v159
	global_load_dwordx4 v[156:159], v164, s[98:99] nt
	s_waitcnt vmcnt(21)
	v_pk_fma_f32 v[160:161], v[40:41], v[84:85], v[160:161]
	v_pk_fma_f32 v[162:163], v[42:43], v[86:87], v[162:163]
	global_store_dwordx4 v165, v[160:163], s[66:67] offset:64 nt
	v_pk_mul_f32 v[40:41], v[160:161], v[188:189]
	v_pk_mul_f32 v[42:43], v[162:163], v[190:191]
	v_cvt_pk_bf16_f32 v40, v40, v41
	v_cvt_pk_bf16_f32 v41, v42, v43
	global_store_dwordx2 v173, v[40:41], s[8:9] offset:32
	v_fmac_f32_e32 v46, v160, v160
	v_fmac_f32_e32 v46, v161, v161
	v_fmac_f32_e32 v46, v162, v162
	v_fmac_f32_e32 v46, v163, v163
	global_load_dwordx4 v[160:163], v164, s[98:99] offset:64 nt
	s_waitcnt vmcnt(21)
; __device__ __forceinline__ unsigned cvt_pk_bf16(float lo, float hi) { unsigned r; asm volatile("v_cvt_pk_bf16_f32 %0, %1, %2" : "=v"(r) : "v"(lo), "v"(hi)); return r; }
;     __device__ __forceinline__ void operator()(const f32x4 (&acc)[2][2][4][2], const Unit& u, int wr, int wc, int fr, int fq) const {
;     ...
;         for (int ai = 0; ai < 2; ++ai)
; #pragma unroll
;             for (int m = 0; m < 4; ++m) { const int row = row0 + ai * HALF + m * 16; const size_t off = (size_t)row * 2048 + col0; float ss = 0.f;
; #pragma unroll
;                 for (int bj = 0; bj < 2; ++bj)
; #pragma unroll
;                     for (int n = 0; n < 2; ++n) { const f32x4 bs = __builtin_nontemporal_load((const f32x4*)(base + off + bj * HALF + n * 16)); const f32x4 x1 = bs + gv[bj][n] * acc[ai][bj][m][n];
;                         *(f32x4*)(out + off + bj * HALF + n * 16) = x1; ss += (x1.x * x1.x + x1.y * x1.y) + (x1.z * x1.z + x1.w * x1.w);
;                         const f32x4 hh = x1 * Gv[bj][n]; u32x2 w; w.x = cvt_pk_bf16(hh.x, hh.y); w.y = cvt_pk_bf16(hh.z, hh.w); *(u32x2*)(A2 + off + bj * HALF + n * 16) = w; }
	v_pk_fma_f32 v[174:175], v[36:37], v[92:93], v[174:175]
	v_pk_fma_f32 v[176:177], v[38:39], v[94:95], v[176:177]
	global_store_dwordx4 v165, v[174:177], s[66:67] offset:512 nt
	v_pk_mul_f32 v[36:37], v[174:175], v[192:193]
	v_pk_mul_f32 v[38:39], v[176:177], v[194:195]
	v_cvt_pk_bf16_f32 v36, v36, v37
	v_cvt_pk_bf16_f32 v37, v38, v39
	global_store_dwordx2 v173, v[36:37], s[8:9] offset:256
	v_fmac_f32_e32 v46, v174, v174
	v_fmac_f32_e32 v46, v175, v175
	v_fmac_f32_e32 v46, v176, v176
	v_fmac_f32_e32 v46, v177, v177
	global_load_dwordx4 v[174:177], v164, s[98:99] offset:512 nt
	s_waitcnt vmcnt(21)
	v_pk_fma_f32 v[178:179], v[32:33], v[96:97], v[178:179]
	v_pk_fma_f32 v[180:181], v[34:35], v[98:99], v[180:181]
	global_store_dwordx4 v165, v[178:181], s[66:67] offset:576 nt
	v_pk_mul_f32 v[32:33], v[178:179], v[196:197]
	v_pk_mul_f32 v[34:35], v[180:181], v[198:199]
	v_cvt_pk_bf16_f32 v32, v32, v33
	v_cvt_pk_bf16_f32 v33, v34, v35
	global_store_dwordx2 v173, v[32:33], s[8:9] offset:288
	v_fmac_f32_e32 v46, v178, v178
	v_fmac_f32_e32 v46, v179, v179
	v_fmac_f32_e32 v46, v180, v180
	v_fmac_f32_e32 v46, v181, v181
	v_add_u32_e32 v165, 0x20000, v165
	v_lshrrev_b32_e32 v173, 1, v165
	global_load_dwordx4 v[178:181], v164, s[98:99] offset:576 nt
	s_waitcnt vmcnt(21)
	v_pk_fma_f32 v[200:201], v[28:29], v[72:73], v[200:201]
	v_pk_fma_f32 v[202:203], v[30:31], v[74:75], v[202:203]
	global_store_dwordx4 v165, v[200:203], s[66:67] nt
	v_pk_mul_f32 v[28:29], v[200:201], v[182:183]
	v_pk_mul_f32 v[30:31], v[202:203], v[184:185]
	v_cvt_pk_bf16_f32 v28, v28, v29
	v_cvt_pk_bf16_f32 v29, v30, v31
	global_store_dwordx2 v173, v[28:29], s[8:9]
	v_mul_f32_e32 v30, v200, v200
	v_fmac_f32_e32 v30, v201, v201
	v_fmac_f32_e32 v30, v202, v202
	v_fmac_f32_e32 v30, v203, v203
	s_waitcnt vmcnt(20)
	v_pk_fma_f32 v[204:205], v[24:25], v[84:85], v[204:205]
	v_pk_fma_f32 v[206:207], v[26:27], v[86:87], v[206:207]
	global_store_dwordx4 v165, v[204:207], s[66:67] offset:64 nt
	v_pk_mul_f32 v[24:25], v[204:205], v[188:189]
	v_pk_mul_f32 v[26:27], v[206:207], v[190:191]
	v_cvt_pk_bf16_f32 v24, v24, v25
	v_cvt_pk_bf16_f32 v25, v26, v27
	global_store_dwordx2 v173, v[24:25], s[8:9] offset:32
	v_fmac_f32_e32 v30, v204, v204
	v_fmac_f32_e32 v30, v205, v205
	v_fmac_f32_e32 v30, v206, v206
	v_fmac_f32_e32 v30, v207, v207
	s_waitcnt vmcnt(19)
	v_pk_fma_f32 v[208:209], v[20:21], v[92:93], v[208:209]
	v_pk_fma_f32 v[210:211], v[22:23], v[94:95], v[210:211]
	global_store_dwordx4 v165, v[208:211], s[66:67] offset:512 nt
	v_pk_mul_f32 v[20:21], v[208:209], v[192:193]
	v_pk_mul_f32 v[22:23], v[210:211], v[194:195]
	v_cvt_pk_bf16_f32 v20, v20, v21
	v_cvt_pk_bf16_f32 v21, v22, v23
	global_store_dwordx2 v173, v[20:21], s[8:9] offset:256
	v_fmac_f32_e32 v30, v208, v208
	v_fmac_f32_e32 v30, v209, v209
	v_fmac_f32_e32 v30, v210, v210
	v_fmac_f32_e32 v30, v211, v211
	s_waitcnt vmcnt(18)
	v_pk_fma_f32 v[212:213], v[16:17], v[96:97], v[212:213]
	v_pk_fma_f32 v[214:215], v[18:19], v[98:99], v[214:215]
	global_store_dwordx4 v165, v[212:215], s[66:67] offset:576 nt
	v_pk_mul_f32 v[16:17], v[212:213], v[196:197]
	v_pk_mul_f32 v[18:19], v[214:215], v[198:199]
	v_cvt_pk_bf16_f32 v16, v16, v17
	v_cvt_pk_bf16_f32 v17, v18, v19
	global_store_dwordx2 v173, v[16:17], s[8:9] offset:288
	v_fmac_f32_e32 v30, v212, v212
	v_fmac_f32_e32 v30, v213, v213
	v_fmac_f32_e32 v30, v214, v214
	v_fmac_f32_e32 v30, v215, v215
	v_add_u32_e32 v165, 0x20000, v165
	v_lshrrev_b32_e32 v173, 1, v165
	s_waitcnt vmcnt(17)
; __device__ __forceinline__ unsigned cvt_pk_bf16(float lo, float hi) { unsigned r; asm volatile("v_cvt_pk_bf16_f32 %0, %1, %2" : "=v"(r) : "v"(lo), "v"(hi)); return r; }
;     __device__ __forceinline__ void operator()(const f32x4 (&acc)[2][2][4][2], const Unit& u, int wr, int wc, int fr, int fq) const {
;     ...
;             for (int m = 0; m < 4; ++m) { const int row = row0 + ai * HALF + m * 16; const size_t off = (size_t)row * 2048 + col0; float ss = 0.f;
; #pragma unroll
;                 for (int bj = 0; bj < 2; ++bj)
; #pragma unroll
;                     for (int n = 0; n < 2; ++n) { const f32x4 bs = __builtin_nontemporal_load((const f32x4*)(base + off + bj * HALF + n * 16)); const f32x4 x1 = bs + gv[bj][n] * acc[ai][bj][m][n];
;                         *(f32x4*)(out + off + bj * HALF + n * 16) = x1; ss += (x1.x * x1.x + x1.y * x1.y) + (x1.z * x1.z + x1.w * x1.w);
;                         const f32x4 hh = x1 * Gv[bj][n]; u32x2 w; w.x = cvt_pk_bf16(hh.x, hh.y); w.y = cvt_pk_bf16(hh.z, hh.w); *(u32x2*)(A2 + off + bj * HALF + n * 16) = w; }
;                 ss += __shfl_xor(ss, 16); ss += __shfl_xor(ss, 32);
;                 if (fq == 0) prow[row] = ss; }
	v_pk_fma_f32 v[156:157], v[12:13], v[72:73], v[156:157]
	v_pk_fma_f32 v[158:159], v[14:15], v[74:75], v[158:159]
	global_store_dwordx4 v165, v[156:159], s[66:67] nt
	v_pk_mul_f32 v[12:13], v[156:157], v[182:183]
	v_pk_mul_f32 v[14:15], v[158:159], v[184:185]
	v_cvt_pk_bf16_f32 v12, v12, v13
	v_cvt_pk_bf16_f32 v13, v14, v15
	global_store_dwordx2 v173, v[12:13], s[8:9]
	v_mul_f32_e32 v14, v156, v156
	v_fmac_f32_e32 v14, v157, v157
	v_fmac_f32_e32 v14, v158, v158
	v_fmac_f32_e32 v14, v159, v159
	s_waitcnt vmcnt(16)
	v_pk_fma_f32 v[160:161], v[8:9], v[84:85], v[160:161]
	v_pk_fma_f32 v[162:163], v[10:11], v[86:87], v[162:163]
	global_store_dwordx4 v165, v[160:163], s[66:67] offset:64 nt
	v_pk_mul_f32 v[8:9], v[160:161], v[188:189]
	v_pk_mul_f32 v[10:11], v[162:163], v[190:191]
	v_cvt_pk_bf16_f32 v8, v8, v9
	v_cvt_pk_bf16_f32 v9, v10, v11
	global_store_dwordx2 v173, v[8:9], s[8:9] offset:32
	v_fmac_f32_e32 v14, v160, v160
	v_fmac_f32_e32 v14, v161, v161
	v_fmac_f32_e32 v14, v162, v162
	v_fmac_f32_e32 v14, v163, v163
	s_waitcnt vmcnt(15)
	v_pk_fma_f32 v[174:175], v[4:5], v[92:93], v[174:175]
	v_pk_fma_f32 v[176:177], v[6:7], v[94:95], v[176:177]
	global_store_dwordx4 v165, v[174:177], s[66:67] offset:512 nt
	v_pk_mul_f32 v[4:5], v[174:175], v[192:193]
	v_pk_mul_f32 v[6:7], v[176:177], v[194:195]
	v_cvt_pk_bf16_f32 v4, v4, v5
	v_cvt_pk_bf16_f32 v5, v6, v7
	global_store_dwordx2 v173, v[4:5], s[8:9] offset:256
	v_fmac_f32_e32 v14, v174, v174
	v_fmac_f32_e32 v14, v175, v175
	v_fmac_f32_e32 v14, v176, v176
	v_fmac_f32_e32 v14, v177, v177
	s_waitcnt vmcnt(14)
	v_pk_fma_f32 v[178:179], v[0:1], v[96:97], v[178:179]
	v_pk_fma_f32 v[180:181], v[2:3], v[98:99], v[180:181]
	global_store_dwordx4 v165, v[178:181], s[66:67] offset:576 nt
	v_pk_mul_f32 v[0:1], v[178:179], v[196:197]
	v_pk_mul_f32 v[2:3], v[180:181], v[198:199]
	v_cvt_pk_bf16_f32 v0, v0, v1
	v_cvt_pk_bf16_f32 v1, v2, v3
	global_store_dwordx2 v173, v[0:1], s[8:9] offset:288
	v_fmac_f32_e32 v14, v178, v178
	v_fmac_f32_e32 v14, v179, v179
	v_fmac_f32_e32 v14, v180, v180
	v_fmac_f32_e32 v14, v181, v181
	ds_bpermute_b32 v143, v216, v142
	ds_bpermute_b32 v127, v216, v126
	ds_bpermute_b32 v111, v216, v110
	ds_bpermute_b32 v83, v216, v82
	ds_bpermute_b32 v63, v216, v62
	ds_bpermute_b32 v47, v216, v46
	ds_bpermute_b32 v31, v216, v30
	ds_bpermute_b32 v15, v216, v14
	s_waitcnt lgkmcnt(0)
	v_add_f32_e32 v142, v142, v143
	v_add_f32_e32 v126, v126, v127
	v_add_f32_e32 v110, v110, v111
	v_add_f32_e32 v82, v82, v83
	v_add_f32_e32 v62, v62, v63
	v_add_f32_e32 v46, v46, v47
	v_add_f32_e32 v30, v30, v31
	v_add_f32_e32 v14, v14, v15
	ds_bpermute_b32 v143, v217, v142
	ds_bpermute_b32 v127, v217, v126
	ds_bpermute_b32 v111, v217, v110
	ds_bpermute_b32 v83, v217, v82
	ds_bpermute_b32 v63, v217, v62
	ds_bpermute_b32 v47, v217, v46
	ds_bpermute_b32 v31, v217, v30
	ds_bpermute_b32 v15, v217, v14
	s_lshl_b32 s25, s34, 2
	s_or_b32 s25, s25, s47
	s_lshl_b32 s25, s25, 16
	v_lshl_add_u32 v164, s36, 8, v166
	v_lshl_add_u32 v164, v164, 2, s25
	s_waitcnt lgkmcnt(0)
	v_add_f32_e32 v142, v142, v143
	v_add_f32_e32 v126, v126, v127
	v_add_f32_e32 v110, v110, v111
	v_add_f32_e32 v82, v82, v83
	v_add_f32_e32 v62, v62, v63
	v_add_f32_e32 v46, v46, v47
	v_add_f32_e32 v30, v30, v31
	v_add_f32_e32 v14, v14, v15
	s_and_saveexec_b64 s[100:101], s[4:5]
	global_store_dword v164, v142, s[48:49]
	global_store_dword v164, v126, s[48:49] offset:64
	global_store_dword v164, v110, s[48:49] offset:128
	global_store_dword v164, v82, s[48:49] offset:192
	global_store_dword v164, v62, s[48:49] offset:512
	global_store_dword v164, v46, s[48:49] offset:576
	global_store_dword v164, v30, s[48:49] offset:640
	global_store_dword v164, v14, s[48:49] offset:704
	s_or_b64 exec, exec, s[100:101]
	s_andn2_b64 vcc, exec, s[6:7]
	s_mov_b64 s[6:7], -1
	s_cbranch_vccnz .LBB0_886
	s_andn2_b64 vcc, exec, s[10:11]
	s_cbranch_vccnz .LBB0_885
	s_barrier
	s_branch .LBB0_885

; __device__ __forceinline__ unsigned cvt_pk_bf16(float lo, float hi) { unsigned r; asm volatile("v_cvt_pk_bf16_f32 %0, %1, %2" : "=v"(r) : "v"(lo), "v"(hi)); return r; }
;     __device__ __forceinline__ void operator()(const f32x4 (&acc)[2][2][4][2], const Unit& u, int wr, int wc, int fr, int fq) const {
;         const int row0 = u.pm * BM + wr * 64 + fr, col0 = u.pn * BM + wc * 32 + 8 * fq, b = (u.pm * BM) >> 12;
;         f32x4 cbv[2][2];
; #pragma unroll
;         for (int bj = 0; bj < 2; ++bj)
; #pragma unroll
;             for (int n = 0; n < 2; ++n) cbv[bj][n] = *(const f32x4*)(cb + (size_t)b * 8192 + col0 + bj * HALF + 4 * n);
; #pragma unroll
;         for (int ai = 0; ai < 2; ++ai)
; #pragma unroll
;             for (int m = 0; m < 4; ++m) { const int rl = wr * 64 + fr + ai * HALF + m * 16; bf16_t* rowp = O + (size_t)(u.pm * BM + rl) * ldc + col0;
;                 const float rs = rstd[((u.pm >> 2) & 1) * 256 + rl];
; #pragma unroll
;                 for (int bj = 0; bj < 2; ++bj) { float v[8];
; #pragma unroll
;                     for (int e = 0; e < 8; ++e) { const float x = fmaxf(acc[ai][bj][m][e >> 2][e & 3] * rs + cbv[bj][e >> 2][e & 3], 0.f); v[e] = x * x; }
;                     u32x4 w; w.x = cvt_pk_bf16(v[0], v[1]); w.y = cvt_pk_bf16(v[2], v[3]); w.z = cvt_pk_bf16(v[4], v[5]); w.w = cvt_pk_bf16(v[6], v[7]);
;                     *(u32x4*)(rowp + bj * HALF) = w; } }
.LBB0_997:
	s_ashr_i32 s24, s22, 4
	s_ashr_i32 s25, s24, 31
	s_lshl_b64 s[24:25], s[24:25], 15
	v_lshl_or_b32 v160, s42, 8, v171
	s_add_u32 s24, s36, s24
	s_addc_u32 s25, s37, s25
	v_ashrrev_i32_e32 v161, 31, v160
	v_lshl_add_u64 v[128:129], v[160:161], 2, s[24:25]
	global_load_dwordx4 v[140:143], v[128:129], off
	global_load_dwordx4 v[136:139], v[128:129], off offset:16
	global_load_dwordx4 v[132:135], v[128:129], off offset:512
	s_nop 0
	global_load_dwordx4 v[128:131], v[128:129], off offset:528
	s_lshl_b32 s15, s22, 8
	s_and_b32 s17, s15, 0x400
	v_add_u32_e32 v176, s17, v172
	ds_read_b32 v177, v176
	v_add_u32_e32 v178, s15, v162
	v_ashrrev_i32_e32 v179, 31, v178
	v_lshlrev_b64 v[178:179], 14, v[178:179]
	v_lshlrev_b64 v[160:161], 1, v[160:161]
	v_lshl_add_u64 v[178:179], s[72:73], 0, v[178:179]
	v_lshl_add_u64 v[178:179], v[178:179], 0, v[160:161]
	v_add_u32_e32 v180, s15, v164
	v_ashrrev_i32_e32 v181, 31, v180
	s_andn2_b64 vcc, exec, s[4:5]
	s_mov_b64 s[4:5], -1
	s_waitcnt vmcnt(0) lgkmcnt(0)
	v_fma_f32 v124, v124, v177, v140
	v_fma_f32 v125, v125, v177, v141
	v_fma_f32 v126, v126, v177, v142
	v_fma_f32 v127, v127, v177, v143
	v_fma_f32 v120, v120, v177, v136
	v_fma_f32 v121, v121, v177, v137
	v_fma_f32 v122, v122, v177, v138
	v_fma_f32 v123, v123, v177, v139
	v_fma_f32 v118, v118, v177, v134
	v_fma_f32 v112, v112, v177, v128
	v_fma_f32 v113, v113, v177, v129
	v_fma_f32 v114, v114, v177, v130
	v_fma_f32 v115, v115, v177, v131
	v_fma_f32 v116, v116, v177, v132
	v_fma_f32 v117, v117, v177, v133
	v_fma_f32 v119, v119, v177, v135
	v_max_f32_e32 v124, 0, v124
	v_max_f32_e32 v125, 0, v125
	v_max_f32_e32 v126, 0, v126
	v_max_f32_e32 v127, 0, v127
	v_max_f32_e32 v120, 0, v120
	v_max_f32_e32 v121, 0, v121
	v_max_f32_e32 v122, 0, v122
	v_max_f32_e32 v123, 0, v123
	v_max_f32_e32 v118, 0, v118
	v_max_f32_e32 v112, 0, v112
	v_max_f32_e32 v113, 0, v113
	v_max_f32_e32 v114, 0, v114
	v_max_f32_e32 v115, 0, v115
	v_max_f32_e32 v116, 0, v116
	v_max_f32_e32 v117, 0, v117
	v_max_f32_e32 v119, 0, v119
	v_mul_f32_e32 v124, v124, v124
	v_mul_f32_e32 v125, v125, v125
	v_mul_f32_e32 v126, v126, v126
	v_mul_f32_e32 v127, v127, v127
	v_mul_f32_e32 v120, v120, v120
	v_mul_f32_e32 v121, v121, v121
	v_mul_f32_e32 v122, v122, v122
	v_mul_f32_e32 v123, v123, v123
	v_mul_f32_e32 v118, v118, v118
	v_mul_f32_e32 v177, v112, v112
	v_mul_f32_e32 v182, v113, v113
	v_mul_f32_e32 v183, v114, v114
	v_mul_f32_e32 v184, v115, v115
	v_cvt_pk_bf16_f32 v112, v124, v125
	v_cvt_pk_bf16_f32 v113, v126, v127
	v_cvt_pk_bf16_f32 v114, v120, v121
	v_cvt_pk_bf16_f32 v115, v122, v123
	v_mul_f32_e32 v116, v116, v116
	v_mul_f32_e32 v117, v117, v117
	v_mul_f32_e32 v119, v119, v119
	global_store_dwordx4 v[178:179], v[112:115], off nt
	s_nop 1
	v_cvt_pk_bf16_f32 v112, v116, v117
	v_cvt_pk_bf16_f32 v113, v118, v119
	v_cvt_pk_bf16_f32 v114, v177, v182
	v_cvt_pk_bf16_f32 v115, v183, v184
	ds_read_b32 v118, v176 offset:64
	global_store_dwordx4 v[178:179], v[112:115], off offset:256 nt
	v_lshlrev_b64 v[116:117], 14, v[180:181]
	v_lshl_add_u64 v[116:117], s[72:73], 0, v[116:117]
	v_lshl_add_u64 v[116:117], v[116:117], 0, v[160:161]
	s_waitcnt lgkmcnt(0)
	v_fma_f32 v104, v104, v118, v136
	v_max_f32_e32 v104, 0, v104
	v_mul_f32_e32 v112, v104, v104
	v_fma_f32 v104, v105, v118, v137
	v_max_f32_e32 v104, 0, v104
	v_mul_f32_e32 v113, v104, v104
	v_fma_f32 v104, v106, v118, v138
	v_max_f32_e32 v104, 0, v104
	v_fma_f32 v108, v108, v118, v140
	v_fma_f32 v109, v109, v118, v141
	v_mul_f32_e32 v114, v104, v104
	v_fma_f32 v104, v107, v118, v139
	v_fma_f32 v110, v110, v118, v142
	v_fma_f32 v111, v111, v118, v143
	v_max_f32_e32 v108, 0, v108
	v_max_f32_e32 v109, 0, v109
	v_max_f32_e32 v104, 0, v104
	v_fma_f32 v96, v96, v118, v128
	v_max_f32_e32 v110, 0, v110
	v_max_f32_e32 v111, 0, v111
	v_mul_f32_e32 v108, v108, v108
	v_mul_f32_e32 v109, v109, v109
	v_mul_f32_e32 v107, v104, v104
	v_cvt_pk_bf16_f32 v104, v108, v109
	v_max_f32_e32 v96, 0, v96
	v_mul_f32_e32 v110, v110, v110
	v_mul_f32_e32 v111, v111, v111
	v_cvt_pk_bf16_f32 v105, v110, v111
	v_cvt_pk_bf16_f32 v106, v112, v113
	v_cvt_pk_bf16_f32 v107, v114, v107
	global_store_dwordx4 v[116:117], v[104:107], off nt
	v_fma_f32 v100, v100, v118, v132
	v_fma_f32 v101, v101, v118, v133
	v_mul_f32_e32 v104, v96, v96
	v_fma_f32 v96, v97, v118, v129
	v_max_f32_e32 v96, 0, v96
	v_mul_f32_e32 v105, v96, v96
	v_fma_f32 v96, v98, v118, v130
	v_max_f32_e32 v96, 0, v96
	v_fma_f32 v102, v102, v118, v134
	v_fma_f32 v103, v103, v118, v135
	v_mul_f32_e32 v106, v96, v96
	v_fma_f32 v96, v99, v118, v131
	v_max_f32_e32 v100, 0, v100
	v_max_f32_e32 v101, 0, v101
	v_max_f32_e32 v102, 0, v102
	v_max_f32_e32 v103, 0, v103
	v_max_f32_e32 v96, 0, v96
	v_mul_f32_e32 v100, v100, v100
	v_mul_f32_e32 v101, v101, v101
	v_mul_f32_e32 v102, v102, v102
	v_mul_f32_e32 v103, v103, v103
	v_mul_f32_e32 v99, v96, v96
	v_cvt_pk_bf16_f32 v96, v100, v101
	v_cvt_pk_bf16_f32 v97, v102, v103
	v_cvt_pk_bf16_f32 v98, v104, v105
	v_cvt_pk_bf16_f32 v99, v106, v99
	global_store_dwordx4 v[116:117], v[96:99], off offset:256 nt
	ds_read_b32 v98, v176 offset:128
	s_waitcnt lgkmcnt(0)
; __device__ __forceinline__ unsigned cvt_pk_bf16(float lo, float hi) { unsigned r; asm volatile("v_cvt_pk_bf16_f32 %0, %1, %2" : "=v"(r) : "v"(lo), "v"(hi)); return r; }
;     __device__ __forceinline__ void operator()(const f32x4 (&acc)[2][2][4][2], const Unit& u, int wr, int wc, int fr, int fq) const {
;     ...
;         for (int ai = 0; ai < 2; ++ai)
; #pragma unroll
;             for (int m = 0; m < 4; ++m) { const int rl = wr * 64 + fr + ai * HALF + m * 16; bf16_t* rowp = O + (size_t)(u.pm * BM + rl) * ldc + col0;
;                 const float rs = rstd[((u.pm >> 2) & 1) * 256 + rl];
; #pragma unroll
;                 for (int bj = 0; bj < 2; ++bj) { float v[8];
; #pragma unroll
;                     for (int e = 0; e < 8; ++e) { const float x = fmaxf(acc[ai][bj][m][e >> 2][e & 3] * rs + cbv[bj][e >> 2][e & 3], 0.f); v[e] = x * x; }
;                     u32x4 w; w.x = cvt_pk_bf16(v[0], v[1]); w.y = cvt_pk_bf16(v[2], v[3]); w.z = cvt_pk_bf16(v[4], v[5]); w.w = cvt_pk_bf16(v[6], v[7]);
;                     *(u32x4*)(rowp + bj * HALF) = w; } }
	v_fma_f32 v88, v88, v98, v136
	v_max_f32_e32 v88, 0, v88
	v_mul_f32_e32 v99, v88, v88
	v_fma_f32 v88, v89, v98, v137
	v_max_f32_e32 v88, 0, v88
	v_add_u32_e32 v96, s15, v165
	v_mul_f32_e32 v100, v88, v88
	v_fma_f32 v88, v90, v98, v138
	v_ashrrev_i32_e32 v97, 31, v96
	v_max_f32_e32 v88, 0, v88
	v_lshlrev_b64 v[96:97], 14, v[96:97]
	v_fma_f32 v92, v92, v98, v140
	v_fma_f32 v93, v93, v98, v141
	v_mul_f32_e32 v101, v88, v88
	v_fma_f32 v88, v91, v98, v139
	v_lshl_add_u64 v[96:97], s[72:73], 0, v[96:97]
	v_max_f32_e32 v92, 0, v92
	v_max_f32_e32 v93, 0, v93
	v_fma_f32 v94, v94, v98, v142
	v_fma_f32 v95, v95, v98, v143
	v_max_f32_e32 v88, 0, v88
	v_fma_f32 v80, v80, v98, v128
	v_lshl_add_u64 v[96:97], v[96:97], 0, v[160:161]
	v_mul_f32_e32 v92, v92, v92
	v_mul_f32_e32 v93, v93, v93
	v_max_f32_e32 v94, 0, v94
	v_max_f32_e32 v95, 0, v95
	v_mul_f32_e32 v91, v88, v88
	v_cvt_pk_bf16_f32 v88, v92, v93
	v_max_f32_e32 v80, 0, v80
	v_mul_f32_e32 v94, v94, v94
	v_mul_f32_e32 v95, v95, v95
	v_cvt_pk_bf16_f32 v89, v94, v95
	v_cvt_pk_bf16_f32 v90, v99, v100
	v_cvt_pk_bf16_f32 v91, v101, v91
	global_store_dwordx4 v[96:97], v[88:91], off nt
	v_fma_f32 v84, v84, v98, v132
	v_fma_f32 v85, v85, v98, v133
	v_mul_f32_e32 v88, v80, v80
	v_fma_f32 v80, v81, v98, v129
	v_max_f32_e32 v80, 0, v80
	v_mul_f32_e32 v89, v80, v80
	v_fma_f32 v80, v82, v98, v130
	v_max_f32_e32 v80, 0, v80
	v_fma_f32 v86, v86, v98, v134
	v_fma_f32 v87, v87, v98, v135
	v_mul_f32_e32 v90, v80, v80
	v_fma_f32 v80, v83, v98, v131
	v_max_f32_e32 v84, 0, v84
	v_max_f32_e32 v85, 0, v85
	v_max_f32_e32 v86, 0, v86
	v_max_f32_e32 v87, 0, v87
	v_max_f32_e32 v80, 0, v80
	v_mul_f32_e32 v84, v84, v84
	v_mul_f32_e32 v85, v85, v85
	v_mul_f32_e32 v86, v86, v86
	v_mul_f32_e32 v87, v87, v87
	v_mul_f32_e32 v83, v80, v80
	v_cvt_pk_bf16_f32 v80, v84, v85
	v_cvt_pk_bf16_f32 v81, v86, v87
	v_cvt_pk_bf16_f32 v82, v88, v89
	v_cvt_pk_bf16_f32 v83, v90, v83
	global_store_dwordx4 v[96:97], v[80:83], off offset:256 nt
	ds_read_b32 v82, v176 offset:192
	s_waitcnt lgkmcnt(0)
	v_fma_f32 v72, v72, v82, v136
	v_max_f32_e32 v72, 0, v72
	v_mul_f32_e32 v83, v72, v72
	v_fma_f32 v72, v73, v82, v137
	v_max_f32_e32 v72, 0, v72
	v_add_u32_e32 v80, s15, v166
	v_mul_f32_e32 v84, v72, v72
	v_fma_f32 v72, v74, v82, v138
	v_ashrrev_i32_e32 v81, 31, v80
	v_max_f32_e32 v72, 0, v72
	v_lshlrev_b64 v[80:81], 14, v[80:81]
	v_fma_f32 v76, v76, v82, v140
	v_fma_f32 v77, v77, v82, v141
	v_mul_f32_e32 v85, v72, v72
	v_fma_f32 v72, v75, v82, v139
	v_lshl_add_u64 v[80:81], s[72:73], 0, v[80:81]
	v_max_f32_e32 v76, 0, v76
	v_max_f32_e32 v77, 0, v77
	v_fma_f32 v78, v78, v82, v142
	v_fma_f32 v79, v79, v82, v143
	v_max_f32_e32 v72, 0, v72
	v_fma_f32 v64, v64, v82, v128
	v_lshl_add_u64 v[80:81], v[80:81], 0, v[160:161]
	v_mul_f32_e32 v76, v76, v76
	v_mul_f32_e32 v77, v77, v77
	v_max_f32_e32 v78, 0, v78
	v_max_f32_e32 v79, 0, v79
	v_mul_f32_e32 v75, v72, v72
	v_cvt_pk_bf16_f32 v72, v76, v77
	v_max_f32_e32 v64, 0, v64
	v_mul_f32_e32 v78, v78, v78
	v_mul_f32_e32 v79, v79, v79
	v_cvt_pk_bf16_f32 v73, v78, v79
	v_cvt_pk_bf16_f32 v74, v83, v84
	v_cvt_pk_bf16_f32 v75, v85, v75
	global_store_dwordx4 v[80:81], v[72:75], off nt
	v_fma_f32 v68, v68, v82, v132
	v_fma_f32 v69, v69, v82, v133
	v_mul_f32_e32 v72, v64, v64
	v_fma_f32 v64, v65, v82, v129
	v_max_f32_e32 v64, 0, v64
	v_mul_f32_e32 v73, v64, v64
	v_fma_f32 v64, v66, v82, v130
	v_max_f32_e32 v64, 0, v64
	v_fma_f32 v70, v70, v82, v134
	v_fma_f32 v71, v71, v82, v135
	v_mul_f32_e32 v74, v64, v64
	v_fma_f32 v64, v67, v82, v131
	v_max_f32_e32 v68, 0, v68
	v_max_f32_e32 v69, 0, v69
	v_max_f32_e32 v70, 0, v70
	v_max_f32_e32 v71, 0, v71
	v_max_f32_e32 v64, 0, v64
	v_mul_f32_e32 v68, v68, v68
	v_mul_f32_e32 v69, v69, v69
	v_mul_f32_e32 v70, v70, v70
	v_mul_f32_e32 v71, v71, v71
	v_mul_f32_e32 v67, v64, v64
	v_cvt_pk_bf16_f32 v64, v68, v69
	v_cvt_pk_bf16_f32 v65, v70, v71
	v_cvt_pk_bf16_f32 v66, v72, v73
	v_cvt_pk_bf16_f32 v67, v74, v67
	global_store_dwordx4 v[80:81], v[64:67], off offset:256 nt
	ds_read_b32 v66, v176 offset:512
	s_waitcnt lgkmcnt(0)
	v_fma_f32 v56, v56, v66, v136
	v_max_f32_e32 v56, 0, v56
	v_mul_f32_e32 v67, v56, v56
	v_fma_f32 v56, v57, v66, v137
	v_max_f32_e32 v56, 0, v56
	v_add_u32_e32 v64, s15, v167
	v_mul_f32_e32 v68, v56, v56
	v_fma_f32 v56, v58, v66, v138
	v_ashrrev_i32_e32 v65, 31, v64
	v_max_f32_e32 v56, 0, v56
	v_lshlrev_b64 v[64:65], 14, v[64:65]
	v_fma_f32 v60, v60, v66, v140
	v_fma_f32 v61, v61, v66, v141
	v_mul_f32_e32 v69, v56, v56
	v_fma_f32 v56, v59, v66, v139
	v_lshl_add_u64 v[64:65], s[72:73], 0, v[64:65]
	v_max_f32_e32 v60, 0, v60
	v_max_f32_e32 v61, 0, v61
	v_fma_f32 v62, v62, v66, v142
	v_fma_f32 v63, v63, v66, v143
	v_max_f32_e32 v56, 0, v56
	v_fma_f32 v48, v48, v66, v128
	v_lshl_add_u64 v[64:65], v[64:65], 0, v[160:161]
	v_mul_f32_e32 v60, v60, v60
	v_mul_f32_e32 v61, v61, v61
	v_max_f32_e32 v62, 0, v62
	v_max_f32_e32 v63, 0, v63
	v_mul_f32_e32 v59, v56, v56
	v_cvt_pk_bf16_f32 v56, v60, v61
	v_max_f32_e32 v48, 0, v48
	v_mul_f32_e32 v62, v62, v62
	v_mul_f32_e32 v63, v63, v63
	v_cvt_pk_bf16_f32 v57, v62, v63
	v_cvt_pk_bf16_f32 v58, v67, v68
	v_cvt_pk_bf16_f32 v59, v69, v59
	global_store_dwordx4 v[64:65], v[56:59], off nt
	v_fma_f32 v52, v52, v66, v132
	v_fma_f32 v53, v53, v66, v133
	v_mul_f32_e32 v56, v48, v48
	v_fma_f32 v48, v49, v66, v129
	v_max_f32_e32 v48, 0, v48
	v_mul_f32_e32 v57, v48, v48
	v_fma_f32 v48, v50, v66, v130
	v_max_f32_e32 v48, 0, v48
	v_fma_f32 v54, v54, v66, v134
	v_fma_f32 v55, v55, v66, v135
	v_mul_f32_e32 v58, v48, v48
	v_fma_f32 v48, v51, v66, v131
	v_max_f32_e32 v52, 0, v52
	v_max_f32_e32 v53, 0, v53
	v_max_f32_e32 v54, 0, v54
	v_max_f32_e32 v55, 0, v55
	v_max_f32_e32 v48, 0, v48
	v_mul_f32_e32 v52, v52, v52
	v_mul_f32_e32 v53, v53, v53
	v_mul_f32_e32 v54, v54, v54
	v_mul_f32_e32 v55, v55, v55
	v_mul_f32_e32 v51, v48, v48
	v_cvt_pk_bf16_f32 v48, v52, v53
	v_cvt_pk_bf16_f32 v49, v54, v55
	v_cvt_pk_bf16_f32 v50, v56, v57
	v_cvt_pk_bf16_f32 v51, v58, v51
	global_store_dwordx4 v[64:65], v[48:51], off offset:256 nt
	ds_read_b32 v50, v176 offset:576
	s_waitcnt lgkmcnt(0)
; __device__ __forceinline__ unsigned cvt_pk_bf16(float lo, float hi) { unsigned r; asm volatile("v_cvt_pk_bf16_f32 %0, %1, %2" : "=v"(r) : "v"(lo), "v"(hi)); return r; }
;     __device__ __forceinline__ void operator()(const f32x4 (&acc)[2][2][4][2], const Unit& u, int wr, int wc, int fr, int fq) const {
;     ...
;         for (int ai = 0; ai < 2; ++ai)
; #pragma unroll
;             for (int m = 0; m < 4; ++m) { const int rl = wr * 64 + fr + ai * HALF + m * 16; bf16_t* rowp = O + (size_t)(u.pm * BM + rl) * ldc + col0;
;                 const float rs = rstd[((u.pm >> 2) & 1) * 256 + rl];
; #pragma unroll
;                 for (int bj = 0; bj < 2; ++bj) { float v[8];
; #pragma unroll
;                     for (int e = 0; e < 8; ++e) { const float x = fmaxf(acc[ai][bj][m][e >> 2][e & 3] * rs + cbv[bj][e >> 2][e & 3], 0.f); v[e] = x * x; }
;                     u32x4 w; w.x = cvt_pk_bf16(v[0], v[1]); w.y = cvt_pk_bf16(v[2], v[3]); w.z = cvt_pk_bf16(v[4], v[5]); w.w = cvt_pk_bf16(v[6], v[7]);
;                     *(u32x4*)(rowp + bj * HALF) = w; } }
	v_fma_f32 v40, v40, v50, v136
	v_max_f32_e32 v40, 0, v40
	v_mul_f32_e32 v51, v40, v40
	v_fma_f32 v40, v41, v50, v137
	v_max_f32_e32 v40, 0, v40
	v_add_u32_e32 v48, s15, v168
	v_mul_f32_e32 v52, v40, v40
	v_fma_f32 v40, v42, v50, v138
	v_ashrrev_i32_e32 v49, 31, v48
	v_max_f32_e32 v40, 0, v40
	v_lshlrev_b64 v[48:49], 14, v[48:49]
	v_fma_f32 v44, v44, v50, v140
	v_fma_f32 v45, v45, v50, v141
	v_mul_f32_e32 v53, v40, v40
	v_fma_f32 v40, v43, v50, v139
	v_lshl_add_u64 v[48:49], s[72:73], 0, v[48:49]
	v_max_f32_e32 v44, 0, v44
	v_max_f32_e32 v45, 0, v45
	v_fma_f32 v46, v46, v50, v142
	v_fma_f32 v47, v47, v50, v143
	v_max_f32_e32 v40, 0, v40
	v_fma_f32 v32, v32, v50, v128
	v_lshl_add_u64 v[48:49], v[48:49], 0, v[160:161]
	v_mul_f32_e32 v44, v44, v44
	v_mul_f32_e32 v45, v45, v45
	v_max_f32_e32 v46, 0, v46
	v_max_f32_e32 v47, 0, v47
	v_mul_f32_e32 v43, v40, v40
	v_cvt_pk_bf16_f32 v40, v44, v45
	v_max_f32_e32 v32, 0, v32
	v_mul_f32_e32 v46, v46, v46
	v_mul_f32_e32 v47, v47, v47
	v_cvt_pk_bf16_f32 v41, v46, v47
	v_cvt_pk_bf16_f32 v42, v51, v52
	v_cvt_pk_bf16_f32 v43, v53, v43
	global_store_dwordx4 v[48:49], v[40:43], off nt
	v_fma_f32 v36, v36, v50, v132
	v_fma_f32 v37, v37, v50, v133
	v_mul_f32_e32 v40, v32, v32
	v_fma_f32 v32, v33, v50, v129
	v_max_f32_e32 v32, 0, v32
	v_mul_f32_e32 v41, v32, v32
	v_fma_f32 v32, v34, v50, v130
	v_max_f32_e32 v32, 0, v32
	v_fma_f32 v38, v38, v50, v134
	v_fma_f32 v39, v39, v50, v135
	v_mul_f32_e32 v42, v32, v32
	v_fma_f32 v32, v35, v50, v131
	v_max_f32_e32 v36, 0, v36
	v_max_f32_e32 v37, 0, v37
	v_max_f32_e32 v38, 0, v38
	v_max_f32_e32 v39, 0, v39
	v_max_f32_e32 v32, 0, v32
	v_mul_f32_e32 v36, v36, v36
	v_mul_f32_e32 v37, v37, v37
	v_mul_f32_e32 v38, v38, v38
	v_mul_f32_e32 v39, v39, v39
	v_mul_f32_e32 v35, v32, v32
	v_cvt_pk_bf16_f32 v32, v36, v37
	v_cvt_pk_bf16_f32 v33, v38, v39
	v_cvt_pk_bf16_f32 v34, v40, v41
	v_cvt_pk_bf16_f32 v35, v42, v35
	global_store_dwordx4 v[48:49], v[32:35], off offset:256 nt
	ds_read_b32 v34, v176 offset:640
	s_waitcnt lgkmcnt(0)
	v_fma_f32 v24, v24, v34, v136
	v_max_f32_e32 v24, 0, v24
	v_mul_f32_e32 v35, v24, v24
	v_fma_f32 v24, v25, v34, v137
	v_max_f32_e32 v24, 0, v24
	v_add_u32_e32 v32, s15, v169
	v_mul_f32_e32 v36, v24, v24
	v_fma_f32 v24, v26, v34, v138
	v_ashrrev_i32_e32 v33, 31, v32
	v_max_f32_e32 v24, 0, v24
	v_lshlrev_b64 v[32:33], 14, v[32:33]
	v_fma_f32 v28, v28, v34, v140
	v_fma_f32 v29, v29, v34, v141
	v_mul_f32_e32 v37, v24, v24
	v_fma_f32 v24, v27, v34, v139
	v_lshl_add_u64 v[32:33], s[72:73], 0, v[32:33]
	v_max_f32_e32 v28, 0, v28
	v_max_f32_e32 v29, 0, v29
	v_fma_f32 v30, v30, v34, v142
	v_fma_f32 v31, v31, v34, v143
	v_max_f32_e32 v24, 0, v24
	v_fma_f32 v16, v16, v34, v128
	v_lshl_add_u64 v[32:33], v[32:33], 0, v[160:161]
	v_mul_f32_e32 v28, v28, v28
	v_mul_f32_e32 v29, v29, v29
	v_max_f32_e32 v30, 0, v30
	v_max_f32_e32 v31, 0, v31
	v_mul_f32_e32 v27, v24, v24
	v_cvt_pk_bf16_f32 v24, v28, v29
	v_max_f32_e32 v16, 0, v16
	v_mul_f32_e32 v30, v30, v30
	v_mul_f32_e32 v31, v31, v31
	v_cvt_pk_bf16_f32 v25, v30, v31
	v_cvt_pk_bf16_f32 v26, v35, v36
	v_cvt_pk_bf16_f32 v27, v37, v27
	global_store_dwordx4 v[32:33], v[24:27], off nt
	v_fma_f32 v20, v20, v34, v132
	v_fma_f32 v21, v21, v34, v133
	v_mul_f32_e32 v24, v16, v16
	v_fma_f32 v16, v17, v34, v129
	v_max_f32_e32 v16, 0, v16
	v_mul_f32_e32 v25, v16, v16
	v_fma_f32 v16, v18, v34, v130
	v_max_f32_e32 v16, 0, v16
	v_fma_f32 v22, v22, v34, v134
	v_fma_f32 v23, v23, v34, v135
	v_mul_f32_e32 v26, v16, v16
	v_fma_f32 v16, v19, v34, v131
	v_max_f32_e32 v20, 0, v20
	v_max_f32_e32 v21, 0, v21
	v_max_f32_e32 v22, 0, v22
	v_max_f32_e32 v23, 0, v23
	v_max_f32_e32 v16, 0, v16
	v_mul_f32_e32 v20, v20, v20
	v_mul_f32_e32 v21, v21, v21
	v_mul_f32_e32 v22, v22, v22
	v_mul_f32_e32 v23, v23, v23
	v_mul_f32_e32 v19, v16, v16
	v_cvt_pk_bf16_f32 v16, v20, v21
	v_cvt_pk_bf16_f32 v17, v22, v23
	v_cvt_pk_bf16_f32 v18, v24, v25
	v_cvt_pk_bf16_f32 v19, v26, v19
	global_store_dwordx4 v[32:33], v[16:19], off offset:256 nt
	ds_read_b32 v18, v176 offset:704
	s_waitcnt lgkmcnt(0)
	v_fma_f32 v8, v8, v18, v136
	v_max_f32_e32 v8, 0, v8
	v_mul_f32_e32 v19, v8, v8
	v_fma_f32 v8, v9, v18, v137
	v_add_u32_e32 v16, s15, v170
	v_max_f32_e32 v8, 0, v8
	v_ashrrev_i32_e32 v17, 31, v16
	v_mul_f32_e32 v20, v8, v8
	v_fma_f32 v8, v10, v18, v138
	v_lshlrev_b64 v[16:17], 14, v[16:17]
	v_fma_f32 v12, v12, v18, v140
	v_fma_f32 v13, v13, v18, v141
	v_max_f32_e32 v8, 0, v8
	v_fmac_f32_e32 v139, v11, v18
	v_lshl_add_u64 v[16:17], s[72:73], 0, v[16:17]
	v_max_f32_e32 v12, 0, v12
	v_max_f32_e32 v13, 0, v13
	v_fma_f32 v14, v14, v18, v142
	v_fmac_f32_e32 v143, v15, v18
	v_mul_f32_e32 v21, v8, v8
	v_max_f32_e32 v8, 0, v139
	v_fma_f32 v0, v0, v18, v128
	v_lshl_add_u64 v[16:17], v[16:17], 0, v[160:161]
	v_mul_f32_e32 v12, v12, v12
	v_mul_f32_e32 v13, v13, v13
	v_max_f32_e32 v14, 0, v14
	v_max_f32_e32 v15, 0, v143
	v_mul_f32_e32 v11, v8, v8
	v_cvt_pk_bf16_f32 v8, v12, v13
	v_max_f32_e32 v0, 0, v0
	v_mul_f32_e32 v14, v14, v14
	v_mul_f32_e32 v15, v15, v15
	v_cvt_pk_bf16_f32 v9, v14, v15
	v_cvt_pk_bf16_f32 v10, v19, v20
	v_cvt_pk_bf16_f32 v11, v21, v11
	global_store_dwordx4 v[16:17], v[8:11], off nt
	v_fmac_f32_e32 v131, v3, v18
	v_fma_f32 v4, v4, v18, v132
	v_mul_f32_e32 v8, v0, v0
	v_fma_f32 v0, v1, v18, v129
	v_max_f32_e32 v0, 0, v0
	v_mul_f32_e32 v9, v0, v0
	v_fma_f32 v0, v2, v18, v130
	v_max_f32_e32 v0, 0, v0
	v_fma_f32 v5, v5, v18, v133
	v_fma_f32 v6, v6, v18, v134
	v_fmac_f32_e32 v135, v7, v18
	v_mul_f32_e32 v10, v0, v0
	v_max_f32_e32 v0, 0, v131
	v_max_f32_e32 v4, 0, v4
	v_max_f32_e32 v5, 0, v5
	v_max_f32_e32 v6, 0, v6
	v_max_f32_e32 v7, 0, v135
	v_mul_f32_e32 v3, v0, v0
	v_mul_f32_e32 v4, v4, v4
	v_mul_f32_e32 v5, v5, v5
	v_mul_f32_e32 v6, v6, v6
	v_mul_f32_e32 v7, v7, v7
	v_cvt_pk_bf16_f32 v0, v4, v5
	v_cvt_pk_bf16_f32 v1, v6, v7
	v_cvt_pk_bf16_f32 v2, v8, v9
	v_cvt_pk_bf16_f32 v3, v10, v3
	global_store_dwordx4 v[16:17], v[0:3], off offset:256 nt
	s_cbranch_vccnz .LBB0_986
	s_andn2_b64 vcc, exec, s[6:7]
	s_cbranch_vccnz .LBB0_985
	s_barrier
	s_branch .LBB0_985

;     __device__ __forceinline__ void operator()(const f32x4 (&acc)[2][2][4][2], const Unit& u, int wr, int wc, int fr, int fq) const {
;         const int row0 = u.pm * BM + wr * 64 + fr, col0 = u.pn * BM + wc * 32 + 4 * fq, b = (u.pm * BM) >> 12;
;         f32x4 gv[2][2];
; #pragma unroll
;         for (int bj = 0; bj < 2; ++bj)
; #pragma unroll
;             for (int n = 0; n < 2; ++n) gv[bj][n] = *(const f32x4*)(gate + (size_t)b * 12288 + col0 + bj * HALF + n * 16);
; #pragma unroll
;         for (int ai = 0; ai < 2; ++ai)
; #pragma unroll
;             for (int m = 0; m < 4; ++m) { const size_t off = (size_t)(row0 + ai * HALF + m * 16) * 2048 + col0;
; #pragma unroll
;                 for (int bj = 0; bj < 2; ++bj)
; #pragma unroll
;                     for (int n = 0; n < 2; ++n) { const f32x4 bs = __builtin_nontemporal_load((const f32x4*)(base + off + bj * HALF + n * 16));
;                         *(f32x4*)(out + off + bj * HALF + n * 16) = bs + gv[bj][n] * acc[ai][bj][m][n]; } }
.LBB0_1074:
	s_ashr_i32 s17, s24, 4
	v_lshl_add_u32 v160, s24, 8, v162
	v_lshl_or_b32 v64, s25, 8, v164
	s_mul_hi_i32 s19, s17, 0xc000
	s_mul_i32 s17, s17, 0xc000
	v_ashrrev_i32_e32 v161, 31, v160
	s_add_u32 s26, s40, s17
	v_ashrrev_i32_e32 v65, 31, v64
	v_lshlrev_b64 v[156:157], 13, v[160:161]
	s_addc_u32 s27, s41, s19
	v_lshlrev_b64 v[158:159], 2, v[64:65]
	v_lshl_add_u64 v[156:157], s[66:67], 0, v[156:157]
	v_lshl_add_u64 v[64:65], s[26:27], 0, v[158:159]
	v_lshl_add_u64 v[156:157], v[156:157], 0, v[158:159]
	global_load_dwordx4 v[128:131], v[64:65], off
	global_load_dwordx4 v[116:119], v[64:65], off offset:64
	global_load_dwordx4 v[108:111], v[64:65], off offset:512
	s_nop 0
	global_load_dwordx4 v[64:67], v[64:65], off offset:576
	s_mov_b64 s[24:25], -1
	s_mov_b64 s[98:99], 0x20000
	s_mov_b64 s[100:101], 0xa0000
	v_mov_b64_e32 v[158:159], v[156:157]
	global_load_dwordx4 v[168:171], v[158:159], off nt
	global_load_dwordx4 v[172:175], v[158:159], off offset:64 nt
	global_load_dwordx4 v[176:179], v[158:159], off offset:512 nt
	global_load_dwordx4 v[180:183], v[158:159], off offset:576 nt
	v_lshl_add_u64 v[158:159], v[158:159], 0, s[98:99]
	global_load_dwordx4 v[184:187], v[158:159], off nt
	global_load_dwordx4 v[188:191], v[158:159], off offset:64 nt
	global_load_dwordx4 v[192:195], v[158:159], off offset:512 nt
	global_load_dwordx4 v[196:199], v[158:159], off offset:576 nt
	v_lshl_add_u64 v[158:159], v[158:159], 0, s[98:99]
	global_load_dwordx4 v[200:203], v[158:159], off nt
	global_load_dwordx4 v[204:207], v[158:159], off offset:64 nt
	global_load_dwordx4 v[208:211], v[158:159], off offset:512 nt
	s_waitcnt vmcnt(10)
	v_pk_fma_f32 v[142:143], v[142:143], v[130:131], v[170:171]
	v_pk_fma_f32 v[140:141], v[140:141], v[128:129], v[168:169]
	global_store_dwordx4 v[156:157], v[140:143], off nt
	global_load_dwordx4 v[168:171], v[158:159], off offset:576 nt
	v_lshl_add_u64 v[158:159], v[158:159], 0, s[98:99]
	s_waitcnt vmcnt(11)
	v_pk_fma_f32 v[138:139], v[138:139], v[118:119], v[174:175]
	v_pk_fma_f32 v[136:137], v[136:137], v[116:117], v[172:173]
	global_store_dwordx4 v[156:157], v[136:139], off offset:64 nt
	global_load_dwordx4 v[172:175], v[158:159], off nt
	s_waitcnt vmcnt(12)
	v_pk_fma_f32 v[134:135], v[134:135], v[110:111], v[178:179]
	v_pk_fma_f32 v[132:133], v[132:133], v[108:109], v[176:177]
	global_store_dwordx4 v[156:157], v[132:135], off offset:512 nt
	global_load_dwordx4 v[176:179], v[158:159], off offset:64 nt
	s_waitcnt vmcnt(13)
	v_pk_fma_f32 v[126:127], v[126:127], v[66:67], v[182:183]
	v_pk_fma_f32 v[124:125], v[124:125], v[64:65], v[180:181]
	global_store_dwordx4 v[156:157], v[124:127], off offset:576 nt
	v_lshl_add_u64 v[156:157], v[156:157], 0, s[98:99]
	global_load_dwordx4 v[180:183], v[158:159], off offset:512 nt
	s_waitcnt vmcnt(14)
	v_pk_fma_f32 v[122:123], v[122:123], v[130:131], v[186:187]
	v_pk_fma_f32 v[120:121], v[120:121], v[128:129], v[184:185]
	global_store_dwordx4 v[156:157], v[120:123], off nt
	global_load_dwordx4 v[184:187], v[158:159], off offset:576 nt
	v_lshl_add_u64 v[158:159], v[158:159], 0, s[100:101]
	s_waitcnt vmcnt(15)
	v_pk_fma_f32 v[114:115], v[114:115], v[118:119], v[190:191]
	v_pk_fma_f32 v[112:113], v[112:113], v[116:117], v[188:189]
	global_store_dwordx4 v[156:157], v[112:115], off offset:64 nt
	global_load_dwordx4 v[188:191], v[158:159], off nt
	s_waitcnt vmcnt(16)
	v_pk_fma_f32 v[106:107], v[106:107], v[110:111], v[194:195]
	v_pk_fma_f32 v[104:105], v[104:105], v[108:109], v[192:193]
	global_store_dwordx4 v[156:157], v[104:107], off offset:512 nt
	global_load_dwordx4 v[192:195], v[158:159], off offset:64 nt
	s_waitcnt vmcnt(17)
	v_pk_fma_f32 v[102:103], v[102:103], v[66:67], v[198:199]
	v_pk_fma_f32 v[100:101], v[100:101], v[64:65], v[196:197]
	global_store_dwordx4 v[156:157], v[100:103], off offset:576 nt
	v_lshl_add_u64 v[156:157], v[156:157], 0, s[98:99]
	global_load_dwordx4 v[196:199], v[158:159], off offset:512 nt
	s_waitcnt vmcnt(18)
	v_pk_fma_f32 v[98:99], v[98:99], v[130:131], v[202:203]
	v_pk_fma_f32 v[96:97], v[96:97], v[128:129], v[200:201]
	global_store_dwordx4 v[156:157], v[96:99], off nt
	global_load_dwordx4 v[200:203], v[158:159], off offset:576 nt
	v_lshl_add_u64 v[158:159], v[158:159], 0, s[98:99]
	s_waitcnt vmcnt(19)
	v_pk_fma_f32 v[94:95], v[94:95], v[118:119], v[206:207]
	v_pk_fma_f32 v[92:93], v[92:93], v[116:117], v[204:205]
	global_store_dwordx4 v[156:157], v[92:95], off offset:64 nt
	global_load_dwordx4 v[204:207], v[158:159], off nt
	s_waitcnt vmcnt(20)
	v_pk_fma_f32 v[90:91], v[90:91], v[110:111], v[210:211]
	v_pk_fma_f32 v[88:89], v[88:89], v[108:109], v[208:209]
	global_store_dwordx4 v[156:157], v[88:91], off offset:512 nt
	global_load_dwordx4 v[208:211], v[158:159], off offset:64 nt
	s_waitcnt vmcnt(20)
	v_pk_fma_f32 v[86:87], v[86:87], v[66:67], v[170:171]
	v_pk_fma_f32 v[84:85], v[84:85], v[64:65], v[168:169]
	global_store_dwordx4 v[156:157], v[84:87], off offset:576 nt
	v_lshl_add_u64 v[156:157], v[156:157], 0, s[98:99]
	global_load_dwordx4 v[168:171], v[158:159], off offset:512 nt
	s_waitcnt vmcnt(20)
;     __device__ __forceinline__ void operator()(const f32x4 (&acc)[2][2][4][2], const Unit& u, int wr, int wc, int fr, int fq) const {
;     ...
;         for (int ai = 0; ai < 2; ++ai)
; #pragma unroll
;             for (int m = 0; m < 4; ++m) { const size_t off = (size_t)(row0 + ai * HALF + m * 16) * 2048 + col0;
; #pragma unroll
;                 for (int bj = 0; bj < 2; ++bj)
; #pragma unroll
;                     for (int n = 0; n < 2; ++n) { const f32x4 bs = __builtin_nontemporal_load((const f32x4*)(base + off + bj * HALF + n * 16));
;                         *(f32x4*)(out + off + bj * HALF + n * 16) = bs + gv[bj][n] * acc[ai][bj][m][n]; } }
	v_pk_fma_f32 v[82:83], v[82:83], v[130:131], v[174:175]
	v_pk_fma_f32 v[80:81], v[80:81], v[128:129], v[172:173]
	global_store_dwordx4 v[156:157], v[80:83], off nt
	global_load_dwordx4 v[172:175], v[158:159], off offset:576 nt
	v_lshl_add_u64 v[158:159], v[158:159], 0, s[98:99]
	s_waitcnt vmcnt(20)
	v_pk_fma_f32 v[78:79], v[78:79], v[118:119], v[178:179]
	v_pk_fma_f32 v[76:77], v[76:77], v[116:117], v[176:177]
	global_store_dwordx4 v[156:157], v[76:79], off offset:64 nt
	global_load_dwordx4 v[176:179], v[158:159], off nt
	s_waitcnt vmcnt(20)
	v_pk_fma_f32 v[74:75], v[74:75], v[110:111], v[182:183]
	v_pk_fma_f32 v[72:73], v[72:73], v[108:109], v[180:181]
	global_store_dwordx4 v[156:157], v[72:75], off offset:512 nt
	global_load_dwordx4 v[180:183], v[158:159], off offset:64 nt
	s_waitcnt vmcnt(20)
	v_pk_fma_f32 v[70:71], v[70:71], v[66:67], v[186:187]
	v_pk_fma_f32 v[68:69], v[68:69], v[64:65], v[184:185]
	global_store_dwordx4 v[156:157], v[68:71], off offset:576 nt
	v_lshl_add_u64 v[156:157], v[156:157], 0, s[100:101]
	global_load_dwordx4 v[184:187], v[158:159], off offset:512 nt
	s_waitcnt vmcnt(20)
	v_pk_fma_f32 v[62:63], v[62:63], v[130:131], v[190:191]
	v_pk_fma_f32 v[60:61], v[60:61], v[128:129], v[188:189]
	global_store_dwordx4 v[156:157], v[60:63], off nt
	global_load_dwordx4 v[188:191], v[158:159], off offset:576 nt
	v_lshl_add_u64 v[158:159], v[158:159], 0, s[98:99]
	s_waitcnt vmcnt(20)
	v_pk_fma_f32 v[58:59], v[58:59], v[118:119], v[194:195]
	v_pk_fma_f32 v[56:57], v[56:57], v[116:117], v[192:193]
	global_store_dwordx4 v[156:157], v[56:59], off offset:64 nt
	global_load_dwordx4 v[192:195], v[158:159], off nt
	s_waitcnt vmcnt(20)
	v_pk_fma_f32 v[54:55], v[54:55], v[110:111], v[198:199]
	v_pk_fma_f32 v[52:53], v[52:53], v[108:109], v[196:197]
	global_store_dwordx4 v[156:157], v[52:55], off offset:512 nt
	global_load_dwordx4 v[196:199], v[158:159], off offset:64 nt
	s_waitcnt vmcnt(20)
	v_pk_fma_f32 v[50:51], v[50:51], v[66:67], v[202:203]
	v_pk_fma_f32 v[48:49], v[48:49], v[64:65], v[200:201]
	global_store_dwordx4 v[156:157], v[48:51], off offset:576 nt
	v_lshl_add_u64 v[156:157], v[156:157], 0, s[98:99]
	global_load_dwordx4 v[200:203], v[158:159], off offset:512 nt
	s_waitcnt vmcnt(20)
	v_pk_fma_f32 v[46:47], v[46:47], v[130:131], v[206:207]
	v_pk_fma_f32 v[44:45], v[44:45], v[128:129], v[204:205]
	global_store_dwordx4 v[156:157], v[44:47], off nt
	global_load_dwordx4 v[204:207], v[158:159], off offset:576 nt
	s_waitcnt vmcnt(20)
	v_pk_fma_f32 v[42:43], v[42:43], v[118:119], v[210:211]
	v_pk_fma_f32 v[40:41], v[40:41], v[116:117], v[208:209]
	global_store_dwordx4 v[156:157], v[40:43], off offset:64 nt
	s_waitcnt vmcnt(19)
	v_pk_fma_f32 v[38:39], v[38:39], v[110:111], v[170:171]
	v_pk_fma_f32 v[36:37], v[36:37], v[108:109], v[168:169]
	global_store_dwordx4 v[156:157], v[36:39], off offset:512 nt
	s_waitcnt vmcnt(18)
	v_pk_fma_f32 v[34:35], v[34:35], v[66:67], v[174:175]
	v_pk_fma_f32 v[32:33], v[32:33], v[64:65], v[172:173]
	global_store_dwordx4 v[156:157], v[32:35], off offset:576 nt
	v_lshl_add_u64 v[156:157], v[156:157], 0, s[98:99]
	s_waitcnt vmcnt(17)
	v_pk_fma_f32 v[30:31], v[30:31], v[130:131], v[178:179]
	v_pk_fma_f32 v[28:29], v[28:29], v[128:129], v[176:177]
	global_store_dwordx4 v[156:157], v[28:31], off nt
	s_waitcnt vmcnt(16)
	v_pk_fma_f32 v[26:27], v[26:27], v[118:119], v[182:183]
	v_pk_fma_f32 v[24:25], v[24:25], v[116:117], v[180:181]
	global_store_dwordx4 v[156:157], v[24:27], off offset:64 nt
	s_waitcnt vmcnt(15)
	v_pk_fma_f32 v[22:23], v[22:23], v[110:111], v[186:187]
	v_pk_fma_f32 v[20:21], v[20:21], v[108:109], v[184:185]
	global_store_dwordx4 v[156:157], v[20:23], off offset:512 nt
	s_waitcnt vmcnt(14)
	v_pk_fma_f32 v[18:19], v[18:19], v[66:67], v[190:191]
	v_pk_fma_f32 v[16:17], v[16:17], v[64:65], v[188:189]
	global_store_dwordx4 v[156:157], v[16:19], off offset:576 nt
	v_lshl_add_u64 v[156:157], v[156:157], 0, s[98:99]
	s_waitcnt vmcnt(13)
	v_pk_fma_f32 v[14:15], v[14:15], v[130:131], v[194:195]
	v_pk_fma_f32 v[12:13], v[12:13], v[128:129], v[192:193]
	global_store_dwordx4 v[156:157], v[12:15], off nt
	s_waitcnt vmcnt(12)
	v_pk_fma_f32 v[10:11], v[10:11], v[118:119], v[198:199]
	v_pk_fma_f32 v[8:9], v[8:9], v[116:117], v[196:197]
	global_store_dwordx4 v[156:157], v[8:11], off offset:64 nt
	s_waitcnt vmcnt(11)
	v_pk_fma_f32 v[6:7], v[6:7], v[110:111], v[202:203]
	v_pk_fma_f32 v[4:5], v[4:5], v[108:109], v[200:201]
	global_store_dwordx4 v[156:157], v[4:7], off offset:512 nt
	s_waitcnt vmcnt(10)
	v_pk_fma_f32 v[2:3], v[2:3], v[66:67], v[206:207]
	v_pk_fma_f32 v[0:1], v[0:1], v[64:65], v[204:205]
	global_store_dwordx4 v[156:157], v[0:3], off offset:576 nt
	s_andn2_b64 vcc, exec, s[0:1]
	s_cbranch_vccnz .LBB0_1063
	s_andn2_b64 vcc, exec, s[2:3]
	s_cbranch_vccnz .LBB0_1062
	s_barrier
	s_branch .LBB0_1062
